# attention unit epilogue: the 7 serialized sub_norm weight loads are preloaded right after the key loop (no wait ladder)
# speedup vs baseline: 1.0077x; 1.0044x over previous
.Latt_loop:
	s_add_i32 s13, s12, 1
	s_cmp_eq_u32 s12, 2
	s_cselect_b32 s12, 0, s13
	s_mul_i32 s15, s12, 0x4800
	s_mul_i32 s16, s12, 0x6000
	s_add_i32 s16, s16, 0xd800
	s_add_i32 s17, s14, 2
	s_min_u32 s17, s17, s11
	s_lshl_b32 s64, s17, 17
	s_add_u32 s18, s64, s83
	s_mov_b32 s19, 0
	s_add_i32 s14, s14, 1
	v_mov_b32_e32 v250, v251
	v_add3_u32 v251, s15, v236, v210
	v_mov_b32_e32 v252, v215
	v_add_u32_e32 v215, s16, v232
	s_waitcnt lgkmcnt(5)
	v_mfma_f32_32x32x16_bf16 v[98:113], v[238:241], v[134:137], 0
	ds_read_b128 v[238:241], v250 offset:4672
	v_exp_f32_e32 v66, v66
	v_exp_f32_e32 v67, v67
	v_exp_f32_e32 v68, v68
	v_mfma_f32_32x32x16_bf16 v[34:49], v[182:185], v[118:121], v[34:49]
	v_exp_f32_e32 v69, v69
	v_exp_f32_e32 v70, v70
	v_exp_f32_e32 v71, v71
	v_mfma_f32_32x32x16_bf16 v[50:65], v[186:189], v[118:121], v[50:65]
	ds_read_b64_tr_b16 v[182:183], v252 offset:3072
	ds_read_b64_tr_b16 v[184:185], v252 offset:4608
	ds_read_b64_tr_b16 v[186:187], v252 offset:3136
	ds_read_b64_tr_b16 v[188:189], v252 offset:4672
	v_exp_f32_e32 v72, v72
	v_exp_f32_e32 v73, v73
	v_cvt_pk_bf16_f32 v66, v66, v67
	v_cvt_pk_bf16_f32 v67, v68, v69
	v_mfma_f32_16x16x32_bf16 v[170:173], v[130:133], v[118:121], v[170:173]
	v_cvt_pk_bf16_f32 v68, v70, v71
	v_cvt_pk_bf16_f32 v69, v72, v73
	s_waitcnt vmcnt(0)
	v_add_u32_e32 v246, s15, v204
	v_add_u32_e32 v247, s16, v231
	ds_write_b128 v246, v[158:161]
	ds_write_b128 v246, v[162:165] offset:9216
	ds_write_b128 v247, v[150:153]
	ds_write_b128 v247, v[154:157] offset:12288
	v_lshl_add_u64 v[246:247], v[218:219], 0, s[64:65]
	global_load_dwordx4 v[158:161], v[246:247], off
	v_lshl_add_u64 v[248:249], v[218:219], 0, s[18:19]
	global_load_dwordx4 v[162:165], v[248:249], off
	v_lshl_add_u64 v[246:247], v[220:221], 0, s[64:65]
	global_load_dwordx4 v[150:153], v[246:247], off
	v_lshl_add_u64 v[248:249], v[220:221], 0, s[18:19]
	global_load_dwordx4 v[154:157], v[248:249], off
	s_waitcnt lgkmcnt(9)
	v_mfma_f32_32x32x16_bf16 v[98:113], v[242:245], v[138:141], v[98:113]
	ds_read_b128 v[242:245], v250 offset:4704
	v_exp_f32_e32 v82, v82
	v_exp_f32_e32 v83, v83
	v_exp_f32_e32 v84, v84
	v_mfma_f32_32x32x16_bf16 v[2:17], v[174:177], v[66:69], v[2:17]
	v_exp_f32_e32 v85, v85
	v_exp_f32_e32 v86, v86
	v_exp_f32_e32 v87, v87
	v_mfma_f32_32x32x16_bf16 v[18:33], v[178:181], v[66:69], v[18:33]
	v_exp_f32_e32 v88, v88
	v_exp_f32_e32 v89, v89
	v_cvt_pk_bf16_f32 v82, v82, v83
	v_cvt_pk_bf16_f32 v83, v84, v85
	v_mfma_f32_16x16x32_bf16 v[166:169], v[130:133], v[66:69], v[166:169]
	v_cvt_pk_bf16_f32 v84, v86, v87
	v_cvt_pk_bf16_f32 v85, v88, v89
	s_waitcnt lgkmcnt(9)
	v_mfma_f32_32x32x16_bf16 v[114:129], v[238:241], v[142:145], 0
	ds_read_b128 v[238:241], v250 offset:9216
	v_exp_f32_e32 v74, v74
	v_exp_f32_e32 v75, v75
	v_exp_f32_e32 v76, v76
	v_mfma_f32_32x32x16_bf16 v[34:49], v[174:177], v[82:85], v[34:49]
	v_exp_f32_e32 v77, v77
	v_exp_f32_e32 v78, v78
	v_exp_f32_e32 v79, v79
	v_mfma_f32_32x32x16_bf16 v[50:65], v[178:181], v[82:85], v[50:65]
	ds_read_b64_tr_b16 v[174:175], v252 offset:6144
	ds_read_b64_tr_b16 v[176:177], v252 offset:7680
	ds_read_b64_tr_b16 v[178:179], v252 offset:6208
	ds_read_b64_tr_b16 v[180:181], v252 offset:7744
	v_exp_f32_e32 v80, v80
	v_exp_f32_e32 v81, v81
	v_cvt_pk_bf16_f32 v70, v74, v75
	v_cvt_pk_bf16_f32 v71, v76, v77
	v_mfma_f32_16x16x32_bf16 v[170:173], v[130:133], v[82:85], v[170:173]
	v_cvt_pk_bf16_f32 v72, v78, v79
	v_cvt_pk_bf16_f32 v73, v80, v81
	s_waitcnt lgkmcnt(5)
	v_mfma_f32_32x32x16_bf16 v[114:129], v[242:245], v[146:149], v[114:129]
	ds_read_b128 v[242:245], v250 offset:9248
	v_exp_f32_e32 v90, v90
	v_exp_f32_e32 v91, v91
	v_exp_f32_e32 v92, v92
	v_mfma_f32_32x32x16_bf16 v[2:17], v[182:185], v[70:73], v[2:17]
	v_exp_f32_e32 v93, v93
	v_exp_f32_e32 v94, v94
	v_exp_f32_e32 v95, v95
	v_mfma_f32_32x32x16_bf16 v[18:33], v[186:189], v[70:73], v[18:33]
	v_exp_f32_e32 v96, v96
	v_exp_f32_e32 v97, v97
	v_cvt_pk_bf16_f32 v86, v90, v91
	v_cvt_pk_bf16_f32 v87, v92, v93
	v_mfma_f32_16x16x32_bf16 v[166:169], v[130:133], v[70:73], v[166:169]
	v_cvt_pk_bf16_f32 v88, v94, v95
	v_cvt_pk_bf16_f32 v89, v96, v97
	s_waitcnt lgkmcnt(5)
	v_mfma_f32_32x32x16_bf16 v[66:81], v[238:241], v[134:137], 0
	ds_read_b128 v[238:241], v250 offset:9280
	v_exp_f32_e32 v98, v98
	v_exp_f32_e32 v99, v99
	v_exp_f32_e32 v100, v100
	v_mfma_f32_32x32x16_bf16 v[34:49], v[182:185], v[86:89], v[34:49]
	v_exp_f32_e32 v101, v101
	v_exp_f32_e32 v102, v102
	v_exp_f32_e32 v103, v103
	v_mfma_f32_32x32x16_bf16 v[50:65], v[186:189], v[86:89], v[50:65]
	ds_read_b64_tr_b16 v[182:183], v252 offset:9216
	ds_read_b64_tr_b16 v[184:185], v252 offset:10752
	ds_read_b64_tr_b16 v[186:187], v252 offset:9280
	ds_read_b64_tr_b16 v[188:189], v252 offset:10816
	v_exp_f32_e32 v104, v104
	v_exp_f32_e32 v105, v105
	v_cvt_pk_bf16_f32 v98, v98, v99
	v_cvt_pk_bf16_f32 v99, v100, v101
	v_mfma_f32_16x16x32_bf16 v[170:173], v[130:133], v[86:89], v[170:173]
	v_cvt_pk_bf16_f32 v100, v102, v103
	v_cvt_pk_bf16_f32 v101, v104, v105
	s_waitcnt lgkmcnt(5)
	v_mfma_f32_32x32x16_bf16 v[66:81], v[242:245], v[138:141], v[66:81]
	ds_read_b128 v[242:245], v250 offset:9312
	v_exp_f32_e32 v114, v114
	v_exp_f32_e32 v115, v115
	v_exp_f32_e32 v116, v116
	v_mfma_f32_32x32x16_bf16 v[2:17], v[174:177], v[98:101], v[2:17]
	v_exp_f32_e32 v117, v117
	v_exp_f32_e32 v118, v118
	v_exp_f32_e32 v119, v119
	v_mfma_f32_32x32x16_bf16 v[18:33], v[178:181], v[98:101], v[18:33]
	v_exp_f32_e32 v120, v120
	v_exp_f32_e32 v121, v121
	v_cvt_pk_bf16_f32 v114, v114, v115
	v_cvt_pk_bf16_f32 v115, v116, v117
	v_mfma_f32_16x16x32_bf16 v[166:169], v[130:133], v[98:101], v[166:169]
	v_cvt_pk_bf16_f32 v116, v118, v119
	v_cvt_pk_bf16_f32 v117, v120, v121
	s_waitcnt lgkmcnt(5)
	v_mfma_f32_32x32x16_bf16 v[82:97], v[238:241], v[142:145], 0
	ds_read_b128 v[238:241], v250 offset:13824
	v_exp_f32_e32 v106, v106
	v_exp_f32_e32 v107, v107
	v_exp_f32_e32 v108, v108
	v_mfma_f32_32x32x16_bf16 v[34:49], v[174:177], v[114:117], v[34:49]
	v_exp_f32_e32 v109, v109
	v_exp_f32_e32 v110, v110
	v_exp_f32_e32 v111, v111
	v_mfma_f32_32x32x16_bf16 v[50:65], v[178:181], v[114:117], v[50:65]
	ds_read_b64_tr_b16 v[174:175], v252 offset:12288
	ds_read_b64_tr_b16 v[176:177], v252 offset:13824
	ds_read_b64_tr_b16 v[178:179], v252 offset:12352
	ds_read_b64_tr_b16 v[180:181], v252 offset:13888
	v_exp_f32_e32 v112, v112
	v_exp_f32_e32 v113, v113
	v_cvt_pk_bf16_f32 v102, v106, v107
	v_cvt_pk_bf16_f32 v103, v108, v109
	v_mfma_f32_16x16x32_bf16 v[170:173], v[130:133], v[114:117], v[170:173]
	v_cvt_pk_bf16_f32 v104, v110, v111
	v_cvt_pk_bf16_f32 v105, v112, v113
	s_waitcnt lgkmcnt(5)
	v_mfma_f32_32x32x16_bf16 v[82:97], v[242:245], v[146:149], v[82:97]
	ds_read_b128 v[242:245], v250 offset:13856
	v_exp_f32_e32 v122, v122
	v_exp_f32_e32 v123, v123
	v_exp_f32_e32 v124, v124
	v_mfma_f32_32x32x16_bf16 v[2:17], v[182:185], v[102:105], v[2:17]
	v_exp_f32_e32 v125, v125
	v_exp_f32_e32 v126, v126
	v_exp_f32_e32 v127, v127
	v_mfma_f32_32x32x16_bf16 v[18:33], v[186:189], v[102:105], v[18:33]
	v_exp_f32_e32 v128, v128
	v_exp_f32_e32 v129, v129
	v_cvt_pk_bf16_f32 v118, v122, v123
	v_cvt_pk_bf16_f32 v119, v124, v125
	v_mfma_f32_16x16x32_bf16 v[166:169], v[130:133], v[102:105], v[166:169]
	v_cvt_pk_bf16_f32 v120, v126, v127
	v_cvt_pk_bf16_f32 v121, v128, v129
	s_waitcnt lgkmcnt(5)
	v_mfma_f32_32x32x16_bf16 v[98:113], v[238:241], v[134:137], 0
	ds_read_b128 v[238:241], v250 offset:13888
	v_exp_f32_e32 v66, v66
	v_exp_f32_e32 v67, v67
	v_exp_f32_e32 v68, v68
	v_mfma_f32_32x32x16_bf16 v[34:49], v[182:185], v[118:121], v[34:49]
	v_exp_f32_e32 v69, v69
	v_exp_f32_e32 v70, v70
	v_exp_f32_e32 v71, v71
	v_mfma_f32_32x32x16_bf16 v[50:65], v[186:189], v[118:121], v[50:65]
	ds_read_b64_tr_b16 v[182:183], v252 offset:15360
	ds_read_b64_tr_b16 v[184:185], v252 offset:16896
	ds_read_b64_tr_b16 v[186:187], v252 offset:15424
	ds_read_b64_tr_b16 v[188:189], v252 offset:16960
	v_exp_f32_e32 v72, v72
	v_exp_f32_e32 v73, v73
	v_cvt_pk_bf16_f32 v66, v66, v67
	v_cvt_pk_bf16_f32 v67, v68, v69
	v_mfma_f32_16x16x32_bf16 v[170:173], v[130:133], v[118:121], v[170:173]
	v_cvt_pk_bf16_f32 v68, v70, v71
	v_cvt_pk_bf16_f32 v69, v72, v73
	s_waitcnt lgkmcnt(5)
	v_mfma_f32_32x32x16_bf16 v[98:113], v[242:245], v[138:141], v[98:113]
	ds_read_b128 v[242:245], v250 offset:13920
	v_exp_f32_e32 v82, v82
	v_exp_f32_e32 v83, v83
	v_exp_f32_e32 v84, v84
	v_mfma_f32_32x32x16_bf16 v[2:17], v[174:177], v[66:69], v[2:17]
	v_exp_f32_e32 v85, v85
	v_exp_f32_e32 v86, v86
	v_exp_f32_e32 v87, v87
	v_mfma_f32_32x32x16_bf16 v[18:33], v[178:181], v[66:69], v[18:33]
	v_exp_f32_e32 v88, v88
	v_exp_f32_e32 v89, v89
	v_cvt_pk_bf16_f32 v82, v82, v83
	v_cvt_pk_bf16_f32 v83, v84, v85
	v_mfma_f32_16x16x32_bf16 v[166:169], v[130:133], v[66:69], v[166:169]
	v_cvt_pk_bf16_f32 v84, v86, v87
	v_cvt_pk_bf16_f32 v85, v88, v89
	s_barrier
	s_waitcnt lgkmcnt(5)
	v_mfma_f32_32x32x16_bf16 v[114:129], v[238:241], v[142:145], 0
	ds_read_b128 v[238:241], v251
	v_exp_f32_e32 v74, v74
	v_exp_f32_e32 v75, v75
	v_exp_f32_e32 v76, v76
	v_mfma_f32_32x32x16_bf16 v[34:49], v[174:177], v[82:85], v[34:49]
	v_exp_f32_e32 v77, v77
	v_exp_f32_e32 v78, v78
	v_exp_f32_e32 v79, v79
	v_mfma_f32_32x32x16_bf16 v[50:65], v[178:181], v[82:85], v[50:65]
	ds_read_b64_tr_b16 v[174:175], v252 offset:18432
	ds_read_b64_tr_b16 v[176:177], v252 offset:19968
	ds_read_b64_tr_b16 v[178:179], v252 offset:18496
	ds_read_b64_tr_b16 v[180:181], v252 offset:20032
	v_exp_f32_e32 v80, v80
	v_exp_f32_e32 v81, v81
	v_cvt_pk_bf16_f32 v70, v74, v75
	v_cvt_pk_bf16_f32 v71, v76, v77
	v_mfma_f32_16x16x32_bf16 v[170:173], v[130:133], v[82:85], v[170:173]
	v_cvt_pk_bf16_f32 v72, v78, v79
	v_cvt_pk_bf16_f32 v73, v80, v81
	s_waitcnt lgkmcnt(5)
	v_mfma_f32_32x32x16_bf16 v[114:129], v[242:245], v[146:149], v[114:129]
	ds_read_b128 v[242:245], v251 offset:32
	v_exp_f32_e32 v90, v90
	v_exp_f32_e32 v91, v91
	v_exp_f32_e32 v92, v92
	v_mfma_f32_32x32x16_bf16 v[2:17], v[182:185], v[70:73], v[2:17]
	v_exp_f32_e32 v93, v93
	v_exp_f32_e32 v94, v94
	v_exp_f32_e32 v95, v95
	v_mfma_f32_32x32x16_bf16 v[18:33], v[186:189], v[70:73], v[18:33]
	v_exp_f32_e32 v96, v96
	v_exp_f32_e32 v97, v97
	v_cvt_pk_bf16_f32 v86, v90, v91
	v_cvt_pk_bf16_f32 v87, v92, v93
	v_mfma_f32_16x16x32_bf16 v[166:169], v[130:133], v[70:73], v[166:169]
	v_cvt_pk_bf16_f32 v88, v94, v95
	v_cvt_pk_bf16_f32 v89, v96, v97
	s_waitcnt lgkmcnt(5)
	v_mfma_f32_32x32x16_bf16 v[66:81], v[238:241], v[134:137], 0
	ds_read_b128 v[238:241], v251 offset:64
	v_exp_f32_e32 v98, v98
	v_exp_f32_e32 v99, v99
	v_exp_f32_e32 v100, v100
	v_mfma_f32_32x32x16_bf16 v[34:49], v[182:185], v[86:89], v[34:49]
	v_exp_f32_e32 v101, v101
	v_exp_f32_e32 v102, v102
	v_exp_f32_e32 v103, v103
	v_mfma_f32_32x32x16_bf16 v[50:65], v[186:189], v[86:89], v[50:65]
	ds_read_b64_tr_b16 v[182:183], v252 offset:21504
	ds_read_b64_tr_b16 v[184:185], v252 offset:23040
	ds_read_b64_tr_b16 v[186:187], v252 offset:21568
	ds_read_b64_tr_b16 v[188:189], v252 offset:23104
	v_exp_f32_e32 v104, v104
	v_exp_f32_e32 v105, v105
	v_cvt_pk_bf16_f32 v98, v98, v99
	v_cvt_pk_bf16_f32 v99, v100, v101
	v_mfma_f32_16x16x32_bf16 v[170:173], v[130:133], v[86:89], v[170:173]
	v_cvt_pk_bf16_f32 v100, v102, v103
	v_cvt_pk_bf16_f32 v101, v104, v105
	s_waitcnt lgkmcnt(5)
	v_mfma_f32_32x32x16_bf16 v[66:81], v[242:245], v[138:141], v[66:81]
	ds_read_b128 v[242:245], v251 offset:96
	v_exp_f32_e32 v114, v114
	v_exp_f32_e32 v115, v115
	v_exp_f32_e32 v116, v116
	v_mfma_f32_32x32x16_bf16 v[2:17], v[174:177], v[98:101], v[2:17]
	v_exp_f32_e32 v117, v117
	v_exp_f32_e32 v118, v118
	v_exp_f32_e32 v119, v119
	v_mfma_f32_32x32x16_bf16 v[18:33], v[178:181], v[98:101], v[18:33]
	v_exp_f32_e32 v120, v120
	v_exp_f32_e32 v121, v121
	v_cvt_pk_bf16_f32 v114, v114, v115
	v_cvt_pk_bf16_f32 v115, v116, v117
	v_mfma_f32_16x16x32_bf16 v[166:169], v[130:133], v[98:101], v[166:169]
	v_cvt_pk_bf16_f32 v116, v118, v119
	v_cvt_pk_bf16_f32 v117, v120, v121
	s_waitcnt lgkmcnt(5)
	v_mfma_f32_32x32x16_bf16 v[82:97], v[238:241], v[142:145], 0
	ds_read_b128 v[238:241], v251 offset:4608
	v_exp_f32_e32 v106, v106
	v_exp_f32_e32 v107, v107
	v_exp_f32_e32 v108, v108
	v_mfma_f32_32x32x16_bf16 v[34:49], v[174:177], v[114:117], v[34:49]
	v_exp_f32_e32 v109, v109
	v_exp_f32_e32 v110, v110
	v_exp_f32_e32 v111, v111
	v_mfma_f32_32x32x16_bf16 v[50:65], v[178:181], v[114:117], v[50:65]
	ds_read_b64_tr_b16 v[174:175], v215
	ds_read_b64_tr_b16 v[176:177], v215 offset:1536
	ds_read_b64_tr_b16 v[178:179], v215 offset:64
	ds_read_b64_tr_b16 v[180:181], v215 offset:1600
	v_exp_f32_e32 v112, v112
	v_exp_f32_e32 v113, v113
	v_cvt_pk_bf16_f32 v102, v106, v107
	v_cvt_pk_bf16_f32 v103, v108, v109
	v_mfma_f32_16x16x32_bf16 v[170:173], v[130:133], v[114:117], v[170:173]
	v_cvt_pk_bf16_f32 v104, v110, v111
	v_cvt_pk_bf16_f32 v105, v112, v113
	s_waitcnt lgkmcnt(5)
	v_mfma_f32_32x32x16_bf16 v[82:97], v[242:245], v[146:149], v[82:97]
	ds_read_b128 v[242:245], v251 offset:4640
	v_exp_f32_e32 v122, v122
	v_exp_f32_e32 v123, v123
	v_exp_f32_e32 v124, v124
	v_mfma_f32_32x32x16_bf16 v[2:17], v[182:185], v[102:105], v[2:17]
	v_exp_f32_e32 v125, v125
	v_exp_f32_e32 v126, v126
	v_exp_f32_e32 v127, v127
	v_mfma_f32_32x32x16_bf16 v[18:33], v[186:189], v[102:105], v[18:33]
	v_exp_f32_e32 v128, v128
	v_exp_f32_e32 v129, v129
	v_cvt_pk_bf16_f32 v118, v122, v123
	v_cvt_pk_bf16_f32 v119, v124, v125
	v_mfma_f32_16x16x32_bf16 v[166:169], v[130:133], v[102:105], v[166:169]
	v_cvt_pk_bf16_f32 v120, v126, v127
	v_cvt_pk_bf16_f32 v121, v128, v129
	s_cmp_lg_u32 s14, s10
	s_cbranch_scc1 .Latt_loop
	s_waitcnt lgkmcnt(0)
	s_nop 1
	v_mfma_f32_16x16x32_bf16 v[170:173], v[130:133], v[118:121], v[170:173]
	v_mfma_f32_32x32x16_bf16 v[34:49], v[182:185], v[118:121], v[34:49]
	v_mfma_f32_32x32x16_bf16 v[50:65], v[186:189], v[118:121], v[50:65]
	s_nop 11
	global_load_dwordx4 v[98:101], v[212:213], off offset:32
	global_load_dwordx4 v[102:105], v[212:213], off offset:64
	global_load_dwordx4 v[106:109], v[212:213], off offset:96
	global_load_dwordx4 v[110:113], v[212:213], off offset:128
	global_load_dwordx4 v[114:117], v[212:213], off offset:160
	global_load_dwordx4 v[122:125], v[212:213], off offset:192
	global_load_dwordx4 v[126:129], v[212:213], off offset:224
	ds_bpermute_b32 v66, v237, v166
	s_nop 3
	ds_bpermute_b32 v67, v237, v170
	s_lshl_b32 s64, s9, 1
	v_mov_b32_e32 v215, v191
	s_mov_b32 s2, 0xf226000
	s_waitcnt lgkmcnt(1)
	v_div_scale_f32 v68, s[10:11], v66, v66, 1.0
	v_rcp_f32_e32 v69, v68
	s_add_i32 s8, s8, 1
	s_cmp_eq_u32 s8, s7
	v_fma_f32 v70, -v68, v69, 1.0
	v_fmac_f32_e32 v69, v70, v69
	v_div_scale_f32 v70, vcc, 1.0, v66, 1.0
	v_mul_f32_e32 v71, v70, v69
	v_fma_f32 v72, -v68, v71, v70
	v_fmac_f32_e32 v71, v72, v69
	v_fma_f32 v68, -v68, v71, v70
	v_div_fmas_f32 v68, v68, v69, v71
	v_div_fixup_f32 v66, v68, v66, 1.0
	s_waitcnt lgkmcnt(0)
	v_div_scale_f32 v68, s[10:11], v67, v67, v230
	v_rcp_f32_e32 v69, v68
	s_mov_b64 s[10:11], 0xf226400
	v_fma_f32 v70, -v68, v69, 1.0
	v_fmac_f32_e32 v69, v70, v69
	v_div_scale_f32 v70, vcc, v230, v67, v230
	v_mul_f32_e32 v71, v70, v69
	v_fma_f32 v72, -v68, v71, v70
	v_fmac_f32_e32 v71, v72, v69
	v_fma_f32 v68, -v68, v71, v70
	v_div_fmas_f32 v68, v68, v69, v71
	v_div_fixup_f32 v68, v68, v67, v230
	v_pk_mul_f32 v[62:63], v[62:63], v[68:69] op_sel_hi:[1,0]
	v_pk_mul_f32 v[34:35], v[34:35], v[68:69] op_sel_hi:[1,0]
	v_pk_fma_f32 v[30:31], v[30:31], v[66:67], v[62:63] op_sel_hi:[1,0,1] neg_lo:[0,0,1] neg_hi:[0,0,1]
	v_pk_mul_f32 v[62:63], v[64:65], v[68:69] op_sel_hi:[1,0]
	v_pk_mul_f32 v[36:37], v[36:37], v[68:69] op_sel_hi:[1,0]
	v_pk_fma_f32 v[32:33], v[32:33], v[66:67], v[62:63] op_sel_hi:[1,0,1] neg_lo:[0,0,1] neg_hi:[0,0,1]
	v_lshlrev_b64 v[62:63], 11, v[216:217]
	v_lshl_add_u64 v[62:63], s[54:55], 0, v[62:63]
	v_lshl_add_u64 v[74:75], v[62:63], 0, s[64:65]
	global_load_dwordx4 v[62:65], v[212:213], off
	v_pk_fma_f32 v[34:35], v[2:3], v[66:67], v[34:35] op_sel_hi:[1,0,1] neg_lo:[0,0,1] neg_hi:[0,0,1]
	v_pk_fma_f32 v[4:5], v[4:5], v[66:67], v[36:37] op_sel_hi:[1,0,1] neg_lo:[0,0,1] neg_hi:[0,0,1]
	v_pk_mul_f32 v[76:77], v[34:35], v[34:35]
	v_pk_mul_f32 v[40:41], v[40:41], v[68:69] op_sel_hi:[1,0]
	v_pk_mul_f32 v[38:39], v[38:39], v[68:69] op_sel_hi:[1,0]
	v_pk_mul_f32 v[44:45], v[44:45], v[68:69] op_sel_hi:[1,0]
	v_pk_mul_f32 v[42:43], v[42:43], v[68:69] op_sel_hi:[1,0]
	v_pk_mul_f32 v[48:49], v[48:49], v[68:69] op_sel_hi:[1,0]
	v_pk_mul_f32 v[46:47], v[46:47], v[68:69] op_sel_hi:[1,0]
	v_pk_mul_f32 v[52:53], v[52:53], v[68:69] op_sel_hi:[1,0]
	v_pk_mul_f32 v[50:51], v[50:51], v[68:69] op_sel_hi:[1,0]
	v_pk_mul_f32 v[56:57], v[56:57], v[68:69] op_sel_hi:[1,0]
	v_pk_mul_f32 v[54:55], v[54:55], v[68:69] op_sel_hi:[1,0]
	v_pk_mul_f32 v[60:61], v[60:61], v[68:69] op_sel_hi:[1,0]
	v_pk_mul_f32 v[58:59], v[58:59], v[68:69] op_sel_hi:[1,0]
	v_pk_mul_f32 v[36:37], v[4:5], v[4:5]
	v_pk_fma_f32 v[8:9], v[8:9], v[66:67], v[40:41] op_sel_hi:[1,0,1] neg_lo:[0,0,1] neg_hi:[0,0,1]
	v_pk_fma_f32 v[38:39], v[6:7], v[66:67], v[38:39] op_sel_hi:[1,0,1] neg_lo:[0,0,1] neg_hi:[0,0,1]
	v_pk_fma_f32 v[12:13], v[12:13], v[66:67], v[44:45] op_sel_hi:[1,0,1] neg_lo:[0,0,1] neg_hi:[0,0,1]
	v_pk_fma_f32 v[10:11], v[10:11], v[66:67], v[42:43] op_sel_hi:[1,0,1] neg_lo:[0,0,1] neg_hi:[0,0,1]
	v_pk_fma_f32 v[16:17], v[16:17], v[66:67], v[48:49] op_sel_hi:[1,0,1] neg_lo:[0,0,1] neg_hi:[0,0,1]
	v_pk_fma_f32 v[14:15], v[14:15], v[66:67], v[46:47] op_sel_hi:[1,0,1] neg_lo:[0,0,1] neg_hi:[0,0,1]
	v_pk_fma_f32 v[20:21], v[20:21], v[66:67], v[52:53] op_sel_hi:[1,0,1] neg_lo:[0,0,1] neg_hi:[0,0,1]
	v_pk_fma_f32 v[18:19], v[18:19], v[66:67], v[50:51] op_sel_hi:[1,0,1] neg_lo:[0,0,1] neg_hi:[0,0,1]
	v_pk_fma_f32 v[24:25], v[24:25], v[66:67], v[56:57] op_sel_hi:[1,0,1] neg_lo:[0,0,1] neg_hi:[0,0,1]
	v_pk_fma_f32 v[22:23], v[22:23], v[66:67], v[54:55] op_sel_hi:[1,0,1] neg_lo:[0,0,1] neg_hi:[0,0,1]
	v_pk_fma_f32 v[28:29], v[28:29], v[66:67], v[60:61] op_sel_hi:[1,0,1] neg_lo:[0,0,1] neg_hi:[0,0,1]
	v_pk_fma_f32 v[26:27], v[26:27], v[66:67], v[58:59] op_sel_hi:[1,0,1] neg_lo:[0,0,1] neg_hi:[0,0,1]
	v_add_f32_e32 v66, v76, v77
	v_add_f32_e32 v36, v36, v66
	v_pk_mul_f32 v[6:7], v[38:39], v[38:39]
	v_add_f32_e32 v36, v37, v36
	v_add_f32_e32 v6, v6, v36
	v_pk_mul_f32 v[40:41], v[8:9], v[8:9]
	v_add_f32_e32 v6, v7, v6
	v_add_f32_e32 v6, v40, v6
	v_pk_mul_f32 v[42:43], v[10:11], v[10:11]
	v_add_f32_e32 v6, v41, v6
	v_add_f32_e32 v6, v42, v6
	v_pk_mul_f32 v[44:45], v[12:13], v[12:13]
	v_add_f32_e32 v6, v43, v6
	v_add_f32_e32 v6, v44, v6
	v_pk_mul_f32 v[46:47], v[14:15], v[14:15]
	v_add_f32_e32 v6, v45, v6
	v_add_f32_e32 v6, v46, v6
	v_pk_mul_f32 v[48:49], v[16:17], v[16:17]
	v_add_f32_e32 v6, v47, v6
	v_add_f32_e32 v6, v48, v6
	v_pk_mul_f32 v[50:51], v[18:19], v[18:19]
	v_add_f32_e32 v6, v49, v6
	v_add_f32_e32 v6, v50, v6
	v_pk_mul_f32 v[52:53], v[20:21], v[20:21]
	v_add_f32_e32 v6, v51, v6
	v_add_f32_e32 v6, v52, v6
	v_pk_mul_f32 v[54:55], v[22:23], v[22:23]
	v_add_f32_e32 v6, v53, v6
	v_add_f32_e32 v6, v54, v6
	v_pk_mul_f32 v[56:57], v[24:25], v[24:25]
	v_add_f32_e32 v6, v55, v6
	v_add_f32_e32 v6, v56, v6
	v_pk_mul_f32 v[58:59], v[26:27], v[26:27]
	v_add_f32_e32 v6, v57, v6
	v_add_f32_e32 v6, v58, v6
	v_pk_mul_f32 v[60:61], v[28:29], v[28:29]
	v_add_f32_e32 v6, v59, v6
	v_add_f32_e32 v6, v60, v6
	v_pk_mul_f32 v[70:71], v[30:31], v[30:31]
	v_add_f32_e32 v6, v61, v6
	v_add_f32_e32 v6, v70, v6
	v_pk_mul_f32 v[72:73], v[32:33], v[32:33]
	v_add_f32_e32 v6, v71, v6
	v_add_f32_e32 v6, v72, v6
	v_add_f32_e32 v6, v73, v6
	ds_bpermute_b32 v7, v229, v6
	v_lshl_add_u64 v[74:75], v[74:75], 0, v[214:215]
	v_lshl_add_u64 v[2:3], v[74:75], 0, s[10:11]
	s_waitcnt lgkmcnt(0)
	v_add_f32_e32 v6, v6, v7
	v_fmamk_f32 v6, v6, 0x3c800000, v192
	v_cmp_gt_f32_e32 vcc, s70, v6
	v_mul_f32_e32 v7, 0x4b800000, v6
	s_nop 0
	v_cndmask_b32_e32 v6, v6, v7, vcc
	v_rsq_f32_e32 v6, v6
	s_nop 0
	v_mul_f32_e32 v7, 0x45800000, v6
	v_cndmask_b32_e32 v6, v6, v7, vcc
	v_mul_f32_e32 v36, v233, v6
	v_pk_mul_f32 v[6:7], v[34:35], v[36:37] op_sel_hi:[1,0]
	v_pk_mul_f32 v[4:5], v[4:5], v[36:37] op_sel_hi:[1,0]
	s_waitcnt vmcnt(0)
	v_pk_mul_f32 v[6:7], v[62:63], v[6:7]
	v_pk_mul_f32 v[4:5], v[64:65], v[4:5]
	v_cvt_pk_bf16_f32 v6, v6, v7
	v_cvt_pk_bf16_f32 v7, v4, v5
	v_add_co_u32_e32 v4, vcc, s2, v74
	v_pk_mul_f32 v[34:35], v[38:39], v[36:37] op_sel_hi:[1,0]
	s_nop 0
	v_addc_co_u32_e32 v5, vcc, 0, v75, vcc
	global_store_dwordx2 v[4:5], v[6:7], off offset:1024
	v_pk_mul_f32 v[8:9], v[8:9], v[36:37] op_sel_hi:[1,0]
	v_mov_b64_e32 v[4:5], v[98:99]
	v_mov_b64_e32 v[6:7], v[100:101]
	v_pk_mul_f32 v[4:5], v[4:5], v[34:35]
	v_pk_mul_f32 v[6:7], v[6:7], v[8:9]
	v_cvt_pk_bf16_f32 v4, v4, v5
	v_cvt_pk_bf16_f32 v5, v6, v7
	global_store_dwordx2 v[2:3], v[4:5], off offset:16
	v_pk_mul_f32 v[8:9], v[10:11], v[36:37] op_sel_hi:[1,0]
	v_mov_b64_e32 v[4:5], v[102:103]
	v_mov_b64_e32 v[6:7], v[104:105]
	v_pk_mul_f32 v[4:5], v[4:5], v[8:9]
	v_pk_mul_f32 v[8:9], v[12:13], v[36:37] op_sel_hi:[1,0]
	v_cvt_pk_bf16_f32 v4, v4, v5
	v_pk_mul_f32 v[6:7], v[6:7], v[8:9]
	v_pk_mul_f32 v[8:9], v[14:15], v[36:37] op_sel_hi:[1,0]
	v_cvt_pk_bf16_f32 v5, v6, v7
	global_store_dwordx2 v[2:3], v[4:5], off offset:32
	v_mov_b64_e32 v[4:5], v[106:107]
	v_mov_b64_e32 v[6:7], v[108:109]
	v_pk_mul_f32 v[4:5], v[4:5], v[8:9]
	v_pk_mul_f32 v[8:9], v[16:17], v[36:37] op_sel_hi:[1,0]
	v_cvt_pk_bf16_f32 v4, v4, v5
	v_pk_mul_f32 v[6:7], v[6:7], v[8:9]
	v_pk_mul_f32 v[8:9], v[18:19], v[36:37] op_sel_hi:[1,0]
	v_cvt_pk_bf16_f32 v5, v6, v7
	global_store_dwordx2 v[2:3], v[4:5], off offset:48
	v_mov_b64_e32 v[4:5], v[110:111]
	v_mov_b64_e32 v[6:7], v[112:113]
	v_pk_mul_f32 v[4:5], v[4:5], v[8:9]
	v_pk_mul_f32 v[8:9], v[20:21], v[36:37] op_sel_hi:[1,0]
	v_cvt_pk_bf16_f32 v4, v4, v5
	v_pk_mul_f32 v[6:7], v[6:7], v[8:9]
	v_pk_mul_f32 v[8:9], v[22:23], v[36:37] op_sel_hi:[1,0]
	v_cvt_pk_bf16_f32 v5, v6, v7
	global_store_dwordx2 v[2:3], v[4:5], off offset:64
	v_mov_b64_e32 v[4:5], v[114:115]
	v_mov_b64_e32 v[6:7], v[116:117]
	v_pk_mul_f32 v[4:5], v[4:5], v[8:9]
	v_pk_mul_f32 v[8:9], v[24:25], v[36:37] op_sel_hi:[1,0]
	v_cvt_pk_bf16_f32 v4, v4, v5
	v_pk_mul_f32 v[6:7], v[6:7], v[8:9]
	v_pk_mul_f32 v[8:9], v[26:27], v[36:37] op_sel_hi:[1,0]
	v_cvt_pk_bf16_f32 v5, v6, v7
	global_store_dwordx2 v[2:3], v[4:5], off offset:80
	v_mov_b64_e32 v[4:5], v[122:123]
	v_mov_b64_e32 v[6:7], v[124:125]
	v_pk_mul_f32 v[4:5], v[4:5], v[8:9]
	v_pk_mul_f32 v[8:9], v[28:29], v[36:37] op_sel_hi:[1,0]
	v_cvt_pk_bf16_f32 v4, v4, v5
	v_pk_mul_f32 v[6:7], v[6:7], v[8:9]
	v_pk_mul_f32 v[8:9], v[30:31], v[36:37] op_sel_hi:[1,0]
	v_cvt_pk_bf16_f32 v5, v6, v7
	global_store_dwordx2 v[2:3], v[4:5], off offset:96
	v_mov_b64_e32 v[4:5], v[126:127]
	v_mov_b64_e32 v[6:7], v[128:129]
	v_pk_mul_f32 v[4:5], v[4:5], v[8:9]
	v_pk_mul_f32 v[8:9], v[32:33], v[36:37] op_sel_hi:[1,0]
	v_cvt_pk_bf16_f32 v4, v4, v5
	v_pk_mul_f32 v[6:7], v[6:7], v[8:9]
	s_nop 0
	v_cvt_pk_bf16_f32 v5, v6, v7
	global_store_dwordx2 v[2:3], v[4:5], off offset:112
	s_cbranch_scc0 .LBB0_745
